# v31 variant: contiguous four-dot read-out chain in the first DPP gap, two V*KP products in each of the other gaps
# baseline (speedup 1.0000x reference)
.LBB0_1238:
	s_or_b64 exec, exec, s[18:19]
	s_waitcnt lgkmcnt(0)
	s_barrier
	s_cmp_lg_u32 s100, 0
	s_cselect_b32 s97, 0x800, 0
	v_add_u32_e32 v167, s97, v114
	ds_read_b128 v[72:75], v114 offset:41216
	ds_read_b128 v[68:71], v114 offset:45312
	ds_read_b128 v[64:67], v114 offset:49408
	ds_read_b128 v[56:59], v114 offset:53504
	ds_read_b128 v[60:63], v167 offset:28928
	ds_read2st64_b32 v[214:215], v115 offset1:1
	s_waitcnt lgkmcnt(0)
	ds_read_b128 v[134:137], v114 offset:41344
	ds_read_b128 v[138:141], v114 offset:45440
	ds_read_b128 v[142:145], v114 offset:49536
	ds_read_b128 v[130:133], v167 offset:29056
	v_dot2_f32_f16 v151, v127, v72, 0
	v_dot2_f32_f16 v151, v126, v73, v151
	v_dot2_f32_f16 v151, v125, v74, v151
	v_dot2_f32_f16 v151, v124, v75, v151
	v_pk_mul_f16 v153, v214, v64
	v_pk_mul_f16 v154, v214, v65
	v_pk_mul_f16 v155, v214, v66
	v_add_f32_dpp v151, v151, v151 quad_perm:[1,0,3,2] row_mask:0xf bank_mask:0xf bound_ctrl:1
	v_pk_mul_f16 v156, v214, v67
	s_nop 0
	v_add_f32_dpp v151, v151, v151 quad_perm:[2,3,0,1] row_mask:0xf bank_mask:0xf bound_ctrl:1
	s_nop 1
	v_add_f32_dpp v151, v151, v151 row_half_mirror row_mask:0xf bank_mask:0xf bound_ctrl:1
	v_cvt_pkrtz_f16_f32 v152, -v151, -v151
	ds_read_b128 v[146:149], v114 offset:53632
	v_pk_fma_f16 v153, v152, v68, v153
	v_pk_fma_f16 v154, v152, v69, v154
	v_pk_fma_f16 v155, v152, v70, v155
	v_pk_fma_f16 v156, v152, v71, v156
	v_pk_fma_f16 v127, v127, v60, v153
	v_pk_fma_f16 v126, v126, v61, v154
	v_pk_fma_f16 v125, v125, v62, v155
	v_pk_fma_f16 v124, v124, v63, v156
	s_waitcnt lgkmcnt(1)
	ds_read_b128 v[72:75], v114 offset:41472
	ds_read_b128 v[68:71], v114 offset:45568
	ds_read_b128 v[64:67], v114 offset:49664
	ds_read_b128 v[60:63], v167 offset:29184
	ds_read2st64_b32 v[216:217], v115 offset0:2 offset1:3
	v_dot2_f32_f16 v151, v127, v134, 0
	v_dot2_f32_f16 v151, v126, v135, v151
	v_dot2_f32_f16 v151, v125, v136, v151
	v_dot2_f32_f16 v151, v124, v137, v151
	v_dot2_f32_f16 v157, v127, v56, 0
	v_dot2_f32_f16 v157, v126, v57, v157
	v_dot2_f32_f16 v157, v125, v58, v157
	v_dot2_f32_f16 v157, v124, v59, v157
	v_add_f32_dpp v151, v151, v151 quad_perm:[1,0,3,2] row_mask:0xf bank_mask:0xf bound_ctrl:1
	v_pk_mul_f16 v153, v215, v142
	v_pk_mul_f16 v154, v215, v143
	v_add_f32_dpp v151, v151, v151 quad_perm:[2,3,0,1] row_mask:0xf bank_mask:0xf bound_ctrl:1
	v_pk_mul_f16 v155, v215, v144
	v_pk_mul_f16 v156, v215, v145
	v_add_f32_dpp v151, v151, v151 row_half_mirror row_mask:0xf bank_mask:0xf bound_ctrl:1
	v_cvt_pkrtz_f16_f32 v152, -v151, -v151
	ds_read_b128 v[56:59], v114 offset:53760
	v_pk_fma_f16 v153, v152, v138, v153
	v_pk_fma_f16 v154, v152, v139, v154
	v_pk_fma_f16 v155, v152, v140, v155
	v_pk_fma_f16 v156, v152, v141, v156
	v_pk_fma_f16 v127, v127, v130, v153
	v_pk_fma_f16 v126, v126, v131, v154
	v_pk_fma_f16 v125, v125, v132, v155
	v_pk_fma_f16 v124, v124, v133, v156
	s_waitcnt lgkmcnt(1)
	ds_read_b128 v[134:137], v114 offset:41600
	ds_read_b128 v[138:141], v114 offset:45696
	ds_read_b128 v[142:145], v114 offset:49792
	ds_read_b128 v[130:133], v167 offset:29312
	v_dot2_f32_f16 v151, v127, v72, 0
	v_dot2_f32_f16 v151, v126, v73, v151
	v_dot2_f32_f16 v151, v125, v74, v151
	v_dot2_f32_f16 v151, v124, v75, v151
	v_dot2_f32_f16 v158, v127, v146, 0
	v_dot2_f32_f16 v158, v126, v147, v158
	v_dot2_f32_f16 v158, v125, v148, v158
	v_dot2_f32_f16 v158, v124, v149, v158
	v_add_f32_dpp v151, v151, v151 quad_perm:[1,0,3,2] row_mask:0xf bank_mask:0xf bound_ctrl:1
	v_pk_mul_f16 v153, v216, v64
	v_pk_mul_f16 v154, v216, v65
	v_add_f32_dpp v151, v151, v151 quad_perm:[2,3,0,1] row_mask:0xf bank_mask:0xf bound_ctrl:1
	v_pk_mul_f16 v155, v216, v66
	v_pk_mul_f16 v156, v216, v67
	v_add_f32_dpp v151, v151, v151 row_half_mirror row_mask:0xf bank_mask:0xf bound_ctrl:1
	v_cvt_pkrtz_f16_f32 v152, -v151, -v151
	ds_read_b128 v[146:149], v114 offset:53888
	ds_write2st64_b32 v116, v157, v158 offset0:0 offset1:8
	v_pk_fma_f16 v153, v152, v68, v153
	v_pk_fma_f16 v154, v152, v69, v154
	v_pk_fma_f16 v155, v152, v70, v155
	v_pk_fma_f16 v156, v152, v71, v156
	v_pk_fma_f16 v127, v127, v60, v153
	v_pk_fma_f16 v126, v126, v61, v154
	v_pk_fma_f16 v125, v125, v62, v155
	v_pk_fma_f16 v124, v124, v63, v156
	s_waitcnt lgkmcnt(2)
	ds_read_b128 v[72:75], v114 offset:41728
	ds_read_b128 v[68:71], v114 offset:45824
	ds_read_b128 v[64:67], v114 offset:49920
	ds_read_b128 v[60:63], v167 offset:29440
	ds_read2st64_b32 v[214:215], v115 offset0:4 offset1:5
	v_dot2_f32_f16 v151, v127, v134, 0
	v_dot2_f32_f16 v151, v126, v135, v151
	v_dot2_f32_f16 v151, v125, v136, v151
	v_dot2_f32_f16 v151, v124, v137, v151
	v_dot2_f32_f16 v157, v127, v56, 0
	v_dot2_f32_f16 v157, v126, v57, v157
	v_dot2_f32_f16 v157, v125, v58, v157
	v_dot2_f32_f16 v157, v124, v59, v157
	v_add_f32_dpp v151, v151, v151 quad_perm:[1,0,3,2] row_mask:0xf bank_mask:0xf bound_ctrl:1
	v_pk_mul_f16 v153, v217, v142
	v_pk_mul_f16 v154, v217, v143
	v_add_f32_dpp v151, v151, v151 quad_perm:[2,3,0,1] row_mask:0xf bank_mask:0xf bound_ctrl:1
	v_pk_mul_f16 v155, v217, v144
	v_pk_mul_f16 v156, v217, v145
	v_add_f32_dpp v151, v151, v151 row_half_mirror row_mask:0xf bank_mask:0xf bound_ctrl:1
	v_cvt_pkrtz_f16_f32 v152, -v151, -v151
	ds_read_b128 v[56:59], v114 offset:54016
	v_pk_fma_f16 v153, v152, v138, v153
	v_pk_fma_f16 v154, v152, v139, v154
	v_pk_fma_f16 v155, v152, v140, v155
	v_pk_fma_f16 v156, v152, v141, v156
	v_pk_fma_f16 v127, v127, v130, v153
	v_pk_fma_f16 v126, v126, v131, v154
	v_pk_fma_f16 v125, v125, v132, v155
	v_pk_fma_f16 v124, v124, v133, v156
	s_waitcnt lgkmcnt(1)
	ds_read_b128 v[134:137], v114 offset:41856
	ds_read_b128 v[138:141], v114 offset:45952
	ds_read_b128 v[142:145], v114 offset:50048
	ds_read_b128 v[130:133], v167 offset:29568
	v_dot2_f32_f16 v151, v127, v72, 0
	v_dot2_f32_f16 v151, v126, v73, v151
	v_dot2_f32_f16 v151, v125, v74, v151
	v_dot2_f32_f16 v151, v124, v75, v151
	v_dot2_f32_f16 v158, v127, v146, 0
	v_dot2_f32_f16 v158, v126, v147, v158
	v_dot2_f32_f16 v158, v125, v148, v158
	v_dot2_f32_f16 v158, v124, v149, v158
	v_add_f32_dpp v151, v151, v151 quad_perm:[1,0,3,2] row_mask:0xf bank_mask:0xf bound_ctrl:1
	v_pk_mul_f16 v153, v214, v64
	v_pk_mul_f16 v154, v214, v65
	v_add_f32_dpp v151, v151, v151 quad_perm:[2,3,0,1] row_mask:0xf bank_mask:0xf bound_ctrl:1
	v_pk_mul_f16 v155, v214, v66
	v_pk_mul_f16 v156, v214, v67
	v_add_f32_dpp v151, v151, v151 row_half_mirror row_mask:0xf bank_mask:0xf bound_ctrl:1
	v_cvt_pkrtz_f16_f32 v152, -v151, -v151
	ds_read_b128 v[146:149], v114 offset:54144
	ds_write2st64_b32 v116, v157, v158 offset0:16 offset1:24
	v_pk_fma_f16 v153, v152, v68, v153
	v_pk_fma_f16 v154, v152, v69, v154
	v_pk_fma_f16 v155, v152, v70, v155
	v_pk_fma_f16 v156, v152, v71, v156
	v_pk_fma_f16 v127, v127, v60, v153
	v_pk_fma_f16 v126, v126, v61, v154
	v_pk_fma_f16 v125, v125, v62, v155
	v_pk_fma_f16 v124, v124, v63, v156
	s_waitcnt lgkmcnt(2)
	ds_read_b128 v[72:75], v114 offset:41984
	ds_read_b128 v[68:71], v114 offset:46080
	ds_read_b128 v[64:67], v114 offset:50176
	ds_read_b128 v[60:63], v167 offset:29696
	ds_read2st64_b32 v[216:217], v115 offset0:6 offset1:7
	v_dot2_f32_f16 v151, v127, v134, 0
	v_dot2_f32_f16 v151, v126, v135, v151
	v_dot2_f32_f16 v151, v125, v136, v151
	v_dot2_f32_f16 v151, v124, v137, v151
	v_dot2_f32_f16 v157, v127, v56, 0
	v_dot2_f32_f16 v157, v126, v57, v157
	v_dot2_f32_f16 v157, v125, v58, v157
	v_dot2_f32_f16 v157, v124, v59, v157
	v_add_f32_dpp v151, v151, v151 quad_perm:[1,0,3,2] row_mask:0xf bank_mask:0xf bound_ctrl:1
	v_pk_mul_f16 v153, v215, v142
	v_pk_mul_f16 v154, v215, v143
	v_add_f32_dpp v151, v151, v151 quad_perm:[2,3,0,1] row_mask:0xf bank_mask:0xf bound_ctrl:1
	v_pk_mul_f16 v155, v215, v144
	v_pk_mul_f16 v156, v215, v145
	v_add_f32_dpp v151, v151, v151 row_half_mirror row_mask:0xf bank_mask:0xf bound_ctrl:1
	v_cvt_pkrtz_f16_f32 v152, -v151, -v151
	ds_read_b128 v[56:59], v114 offset:54272
	v_pk_fma_f16 v153, v152, v138, v153
	v_pk_fma_f16 v154, v152, v139, v154
	v_pk_fma_f16 v155, v152, v140, v155
	v_pk_fma_f16 v156, v152, v141, v156
	v_pk_fma_f16 v127, v127, v130, v153
	v_pk_fma_f16 v126, v126, v131, v154
	v_pk_fma_f16 v125, v125, v132, v155
	v_pk_fma_f16 v124, v124, v133, v156
	s_waitcnt lgkmcnt(1)
	ds_read_b128 v[134:137], v114 offset:42112
	ds_read_b128 v[138:141], v114 offset:46208
	ds_read_b128 v[142:145], v114 offset:50304
	ds_read_b128 v[130:133], v167 offset:29824
	v_dot2_f32_f16 v151, v127, v72, 0
	v_dot2_f32_f16 v151, v126, v73, v151
	v_dot2_f32_f16 v151, v125, v74, v151
	v_dot2_f32_f16 v151, v124, v75, v151
	v_dot2_f32_f16 v158, v127, v146, 0
	v_dot2_f32_f16 v158, v126, v147, v158
	v_dot2_f32_f16 v158, v125, v148, v158
	v_dot2_f32_f16 v158, v124, v149, v158
	v_add_f32_dpp v151, v151, v151 quad_perm:[1,0,3,2] row_mask:0xf bank_mask:0xf bound_ctrl:1
	v_pk_mul_f16 v153, v216, v64
	v_pk_mul_f16 v154, v216, v65
	v_add_f32_dpp v151, v151, v151 quad_perm:[2,3,0,1] row_mask:0xf bank_mask:0xf bound_ctrl:1
	v_pk_mul_f16 v155, v216, v66
	v_pk_mul_f16 v156, v216, v67
	v_add_f32_dpp v151, v151, v151 row_half_mirror row_mask:0xf bank_mask:0xf bound_ctrl:1
	v_cvt_pkrtz_f16_f32 v152, -v151, -v151
	ds_read_b128 v[146:149], v114 offset:54400
	ds_write2st64_b32 v116, v157, v158 offset0:32 offset1:40
	v_pk_fma_f16 v153, v152, v68, v153
	v_pk_fma_f16 v154, v152, v69, v154
	v_pk_fma_f16 v155, v152, v70, v155
	v_pk_fma_f16 v156, v152, v71, v156
	v_pk_fma_f16 v127, v127, v60, v153
	v_pk_fma_f16 v126, v126, v61, v154
	v_pk_fma_f16 v125, v125, v62, v155
	v_pk_fma_f16 v124, v124, v63, v156
	s_waitcnt lgkmcnt(2)
	ds_read_b128 v[72:75], v114 offset:42240
	ds_read_b128 v[68:71], v114 offset:46336
	ds_read_b128 v[64:67], v114 offset:50432
	ds_read_b128 v[60:63], v167 offset:29952
	ds_read2st64_b32 v[214:215], v115 offset0:8 offset1:9
	v_dot2_f32_f16 v151, v127, v134, 0
	v_dot2_f32_f16 v151, v126, v135, v151
	v_dot2_f32_f16 v151, v125, v136, v151
	v_dot2_f32_f16 v151, v124, v137, v151
	v_dot2_f32_f16 v157, v127, v56, 0
	v_dot2_f32_f16 v157, v126, v57, v157
	v_dot2_f32_f16 v157, v125, v58, v157
	v_dot2_f32_f16 v157, v124, v59, v157
	v_add_f32_dpp v151, v151, v151 quad_perm:[1,0,3,2] row_mask:0xf bank_mask:0xf bound_ctrl:1
	v_pk_mul_f16 v153, v217, v142
	v_pk_mul_f16 v154, v217, v143
	v_add_f32_dpp v151, v151, v151 quad_perm:[2,3,0,1] row_mask:0xf bank_mask:0xf bound_ctrl:1
	v_pk_mul_f16 v155, v217, v144
	v_pk_mul_f16 v156, v217, v145
	v_add_f32_dpp v151, v151, v151 row_half_mirror row_mask:0xf bank_mask:0xf bound_ctrl:1
	v_cvt_pkrtz_f16_f32 v152, -v151, -v151
	ds_read_b128 v[56:59], v114 offset:54528
	v_pk_fma_f16 v153, v152, v138, v153
	v_pk_fma_f16 v154, v152, v139, v154
	v_pk_fma_f16 v155, v152, v140, v155
	v_pk_fma_f16 v156, v152, v141, v156
	v_pk_fma_f16 v127, v127, v130, v153
	v_pk_fma_f16 v126, v126, v131, v154
	v_pk_fma_f16 v125, v125, v132, v155
	v_pk_fma_f16 v124, v124, v133, v156
	s_waitcnt lgkmcnt(1)
	ds_read_b128 v[134:137], v114 offset:42368
	ds_read_b128 v[138:141], v114 offset:46464
	ds_read_b128 v[142:145], v114 offset:50560
	ds_read_b128 v[130:133], v167 offset:30080
	v_dot2_f32_f16 v151, v127, v72, 0
	v_dot2_f32_f16 v151, v126, v73, v151
	v_dot2_f32_f16 v151, v125, v74, v151
	v_dot2_f32_f16 v151, v124, v75, v151
	v_dot2_f32_f16 v158, v127, v146, 0
	v_dot2_f32_f16 v158, v126, v147, v158
	v_dot2_f32_f16 v158, v125, v148, v158
	v_dot2_f32_f16 v158, v124, v149, v158
	v_add_f32_dpp v151, v151, v151 quad_perm:[1,0,3,2] row_mask:0xf bank_mask:0xf bound_ctrl:1
	v_pk_mul_f16 v153, v214, v64
	v_pk_mul_f16 v154, v214, v65
	v_add_f32_dpp v151, v151, v151 quad_perm:[2,3,0,1] row_mask:0xf bank_mask:0xf bound_ctrl:1
	v_pk_mul_f16 v155, v214, v66
	v_pk_mul_f16 v156, v214, v67
	v_add_f32_dpp v151, v151, v151 row_half_mirror row_mask:0xf bank_mask:0xf bound_ctrl:1
	v_cvt_pkrtz_f16_f32 v152, -v151, -v151
	ds_read_b128 v[146:149], v114 offset:54656
	ds_write2st64_b32 v116, v157, v158 offset0:48 offset1:56
	v_pk_fma_f16 v153, v152, v68, v153
	v_pk_fma_f16 v154, v152, v69, v154
	v_pk_fma_f16 v155, v152, v70, v155
	v_pk_fma_f16 v156, v152, v71, v156
	v_pk_fma_f16 v127, v127, v60, v153
	v_pk_fma_f16 v126, v126, v61, v154
	v_pk_fma_f16 v125, v125, v62, v155
	v_pk_fma_f16 v124, v124, v63, v156
	s_waitcnt lgkmcnt(2)
	ds_read_b128 v[72:75], v114 offset:42496
	ds_read_b128 v[68:71], v114 offset:46592
	ds_read_b128 v[64:67], v114 offset:50688
	ds_read_b128 v[60:63], v167 offset:30208
	ds_read2st64_b32 v[216:217], v115 offset0:10 offset1:11
	v_dot2_f32_f16 v151, v127, v134, 0
	v_dot2_f32_f16 v151, v126, v135, v151
	v_dot2_f32_f16 v151, v125, v136, v151
	v_dot2_f32_f16 v151, v124, v137, v151
	v_dot2_f32_f16 v157, v127, v56, 0
	v_dot2_f32_f16 v157, v126, v57, v157
	v_dot2_f32_f16 v157, v125, v58, v157
	v_dot2_f32_f16 v157, v124, v59, v157
	v_add_f32_dpp v151, v151, v151 quad_perm:[1,0,3,2] row_mask:0xf bank_mask:0xf bound_ctrl:1
	v_pk_mul_f16 v153, v215, v142
	v_pk_mul_f16 v154, v215, v143
	v_add_f32_dpp v151, v151, v151 quad_perm:[2,3,0,1] row_mask:0xf bank_mask:0xf bound_ctrl:1
	v_pk_mul_f16 v155, v215, v144
	v_pk_mul_f16 v156, v215, v145
	v_add_f32_dpp v151, v151, v151 row_half_mirror row_mask:0xf bank_mask:0xf bound_ctrl:1
	v_cvt_pkrtz_f16_f32 v152, -v151, -v151
	ds_read_b128 v[56:59], v114 offset:54784
	v_pk_fma_f16 v153, v152, v138, v153
	v_pk_fma_f16 v154, v152, v139, v154
	v_pk_fma_f16 v155, v152, v140, v155
	v_pk_fma_f16 v156, v152, v141, v156
	v_pk_fma_f16 v127, v127, v130, v153
	v_pk_fma_f16 v126, v126, v131, v154
	v_pk_fma_f16 v125, v125, v132, v155
	v_pk_fma_f16 v124, v124, v133, v156
	s_waitcnt lgkmcnt(1)
	ds_read_b128 v[134:137], v114 offset:42624
	ds_read_b128 v[138:141], v114 offset:46720
	ds_read_b128 v[142:145], v114 offset:50816
	ds_read_b128 v[130:133], v167 offset:30336
	v_dot2_f32_f16 v151, v127, v72, 0
	v_dot2_f32_f16 v151, v126, v73, v151
	v_dot2_f32_f16 v151, v125, v74, v151
	v_dot2_f32_f16 v151, v124, v75, v151
	v_dot2_f32_f16 v158, v127, v146, 0
	v_dot2_f32_f16 v158, v126, v147, v158
	v_dot2_f32_f16 v158, v125, v148, v158
	v_dot2_f32_f16 v158, v124, v149, v158
	v_add_f32_dpp v151, v151, v151 quad_perm:[1,0,3,2] row_mask:0xf bank_mask:0xf bound_ctrl:1
	v_pk_mul_f16 v153, v216, v64
	v_pk_mul_f16 v154, v216, v65
	v_add_f32_dpp v151, v151, v151 quad_perm:[2,3,0,1] row_mask:0xf bank_mask:0xf bound_ctrl:1
	v_pk_mul_f16 v155, v216, v66
	v_pk_mul_f16 v156, v216, v67
	v_add_f32_dpp v151, v151, v151 row_half_mirror row_mask:0xf bank_mask:0xf bound_ctrl:1
	v_cvt_pkrtz_f16_f32 v152, -v151, -v151
	ds_read_b128 v[146:149], v114 offset:54912
	ds_write2st64_b32 v116, v157, v158 offset0:64 offset1:72
	v_pk_fma_f16 v153, v152, v68, v153
	v_pk_fma_f16 v154, v152, v69, v154
	v_pk_fma_f16 v155, v152, v70, v155
	v_pk_fma_f16 v156, v152, v71, v156
	v_pk_fma_f16 v127, v127, v60, v153
	v_pk_fma_f16 v126, v126, v61, v154
	v_pk_fma_f16 v125, v125, v62, v155
	v_pk_fma_f16 v124, v124, v63, v156
	s_waitcnt lgkmcnt(2)
	ds_read_b128 v[72:75], v114 offset:42752
	ds_read_b128 v[68:71], v114 offset:46848
	ds_read_b128 v[64:67], v114 offset:50944
	ds_read_b128 v[60:63], v167 offset:30464
	ds_read2st64_b32 v[214:215], v115 offset0:12 offset1:13
	v_dot2_f32_f16 v151, v127, v134, 0
	v_dot2_f32_f16 v151, v126, v135, v151
	v_dot2_f32_f16 v151, v125, v136, v151
	v_dot2_f32_f16 v151, v124, v137, v151
	v_dot2_f32_f16 v157, v127, v56, 0
	v_dot2_f32_f16 v157, v126, v57, v157
	v_dot2_f32_f16 v157, v125, v58, v157
	v_dot2_f32_f16 v157, v124, v59, v157
	v_add_f32_dpp v151, v151, v151 quad_perm:[1,0,3,2] row_mask:0xf bank_mask:0xf bound_ctrl:1
	v_pk_mul_f16 v153, v217, v142
	v_pk_mul_f16 v154, v217, v143
	v_add_f32_dpp v151, v151, v151 quad_perm:[2,3,0,1] row_mask:0xf bank_mask:0xf bound_ctrl:1
	v_pk_mul_f16 v155, v217, v144
	v_pk_mul_f16 v156, v217, v145
	v_add_f32_dpp v151, v151, v151 row_half_mirror row_mask:0xf bank_mask:0xf bound_ctrl:1
	v_cvt_pkrtz_f16_f32 v152, -v151, -v151
	ds_read_b128 v[56:59], v114 offset:55040
	v_pk_fma_f16 v153, v152, v138, v153
	v_pk_fma_f16 v154, v152, v139, v154
	v_pk_fma_f16 v155, v152, v140, v155
	v_pk_fma_f16 v156, v152, v141, v156
	v_pk_fma_f16 v127, v127, v130, v153
	v_pk_fma_f16 v126, v126, v131, v154
	v_pk_fma_f16 v125, v125, v132, v155
	v_pk_fma_f16 v124, v124, v133, v156
	s_waitcnt lgkmcnt(1)
	ds_read_b128 v[134:137], v114 offset:42880
	ds_read_b128 v[138:141], v114 offset:46976
	ds_read_b128 v[142:145], v114 offset:51072
	ds_read_b128 v[130:133], v167 offset:30592
	v_dot2_f32_f16 v151, v127, v72, 0
	v_dot2_f32_f16 v151, v126, v73, v151
	v_dot2_f32_f16 v151, v125, v74, v151
	v_dot2_f32_f16 v151, v124, v75, v151
	v_dot2_f32_f16 v158, v127, v146, 0
	v_dot2_f32_f16 v158, v126, v147, v158
	v_dot2_f32_f16 v158, v125, v148, v158
	v_dot2_f32_f16 v158, v124, v149, v158
	v_add_f32_dpp v151, v151, v151 quad_perm:[1,0,3,2] row_mask:0xf bank_mask:0xf bound_ctrl:1
	v_pk_mul_f16 v153, v214, v64
	v_pk_mul_f16 v154, v214, v65
	v_add_f32_dpp v151, v151, v151 quad_perm:[2,3,0,1] row_mask:0xf bank_mask:0xf bound_ctrl:1
	v_pk_mul_f16 v155, v214, v66
	v_pk_mul_f16 v156, v214, v67
	v_add_f32_dpp v151, v151, v151 row_half_mirror row_mask:0xf bank_mask:0xf bound_ctrl:1
	v_cvt_pkrtz_f16_f32 v152, -v151, -v151
	ds_read_b128 v[146:149], v114 offset:55168
	ds_write2st64_b32 v116, v157, v158 offset0:80 offset1:88
	v_pk_fma_f16 v153, v152, v68, v153
	v_pk_fma_f16 v154, v152, v69, v154
	v_pk_fma_f16 v155, v152, v70, v155
	v_pk_fma_f16 v156, v152, v71, v156
	v_pk_fma_f16 v127, v127, v60, v153
	v_pk_fma_f16 v126, v126, v61, v154
	v_pk_fma_f16 v125, v125, v62, v155
	v_pk_fma_f16 v124, v124, v63, v156
	s_waitcnt lgkmcnt(2)
	ds_read_b128 v[72:75], v114 offset:43008
	ds_read_b128 v[68:71], v114 offset:47104
	ds_read_b128 v[64:67], v114 offset:51200
	ds_read_b128 v[60:63], v167 offset:30720
	ds_read2st64_b32 v[216:217], v115 offset0:14 offset1:15
	v_dot2_f32_f16 v151, v127, v134, 0
	v_dot2_f32_f16 v151, v126, v135, v151
	v_dot2_f32_f16 v151, v125, v136, v151
	v_dot2_f32_f16 v151, v124, v137, v151
	v_dot2_f32_f16 v157, v127, v56, 0
	v_dot2_f32_f16 v157, v126, v57, v157
	v_dot2_f32_f16 v157, v125, v58, v157
	v_dot2_f32_f16 v157, v124, v59, v157
	v_add_f32_dpp v151, v151, v151 quad_perm:[1,0,3,2] row_mask:0xf bank_mask:0xf bound_ctrl:1
	v_pk_mul_f16 v153, v215, v142
	v_pk_mul_f16 v154, v215, v143
	v_add_f32_dpp v151, v151, v151 quad_perm:[2,3,0,1] row_mask:0xf bank_mask:0xf bound_ctrl:1
	v_pk_mul_f16 v155, v215, v144
	v_pk_mul_f16 v156, v215, v145
	v_add_f32_dpp v151, v151, v151 row_half_mirror row_mask:0xf bank_mask:0xf bound_ctrl:1
	v_cvt_pkrtz_f16_f32 v152, -v151, -v151
	ds_read_b128 v[56:59], v114 offset:55296
	v_pk_fma_f16 v153, v152, v138, v153
	v_pk_fma_f16 v154, v152, v139, v154
	v_pk_fma_f16 v155, v152, v140, v155
	v_pk_fma_f16 v156, v152, v141, v156
	v_pk_fma_f16 v127, v127, v130, v153
	v_pk_fma_f16 v126, v126, v131, v154
	v_pk_fma_f16 v125, v125, v132, v155
	v_pk_fma_f16 v124, v124, v133, v156
	s_waitcnt lgkmcnt(1)
	ds_read_b128 v[134:137], v114 offset:43136
	ds_read_b128 v[138:141], v114 offset:47232
	ds_read_b128 v[142:145], v114 offset:51328
	ds_read_b128 v[130:133], v167 offset:30848
	v_dot2_f32_f16 v151, v127, v72, 0
	v_dot2_f32_f16 v151, v126, v73, v151
	v_dot2_f32_f16 v151, v125, v74, v151
	v_dot2_f32_f16 v151, v124, v75, v151
	v_dot2_f32_f16 v158, v127, v146, 0
	v_dot2_f32_f16 v158, v126, v147, v158
	v_dot2_f32_f16 v158, v125, v148, v158
	v_dot2_f32_f16 v158, v124, v149, v158
	v_add_f32_dpp v151, v151, v151 quad_perm:[1,0,3,2] row_mask:0xf bank_mask:0xf bound_ctrl:1
	v_pk_mul_f16 v153, v216, v64
	v_pk_mul_f16 v154, v216, v65
	v_add_f32_dpp v151, v151, v151 quad_perm:[2,3,0,1] row_mask:0xf bank_mask:0xf bound_ctrl:1
	v_pk_mul_f16 v155, v216, v66
	v_pk_mul_f16 v156, v216, v67
	v_add_f32_dpp v151, v151, v151 row_half_mirror row_mask:0xf bank_mask:0xf bound_ctrl:1
	v_cvt_pkrtz_f16_f32 v152, -v151, -v151
	ds_read_b128 v[146:149], v114 offset:55424
	ds_write2st64_b32 v116, v157, v158 offset0:96 offset1:104
	v_pk_fma_f16 v153, v152, v68, v153
	v_pk_fma_f16 v154, v152, v69, v154
	v_pk_fma_f16 v155, v152, v70, v155
	v_pk_fma_f16 v156, v152, v71, v156
	v_pk_fma_f16 v127, v127, v60, v153
	v_pk_fma_f16 v126, v126, v61, v154
	v_pk_fma_f16 v125, v125, v62, v155
	v_pk_fma_f16 v124, v124, v63, v156
	s_waitcnt lgkmcnt(0)
	v_dot2_f32_f16 v151, v127, v134, 0
	v_dot2_f32_f16 v151, v126, v135, v151
	v_dot2_f32_f16 v151, v125, v136, v151
	v_dot2_f32_f16 v151, v124, v137, v151
	v_dot2_f32_f16 v157, v127, v56, 0
	v_dot2_f32_f16 v157, v126, v57, v157
	v_dot2_f32_f16 v157, v125, v58, v157
	v_dot2_f32_f16 v157, v124, v59, v157
	v_add_f32_dpp v151, v151, v151 quad_perm:[1,0,3,2] row_mask:0xf bank_mask:0xf bound_ctrl:1
	v_pk_mul_f16 v153, v217, v142
	v_pk_mul_f16 v154, v217, v143
	v_add_f32_dpp v151, v151, v151 quad_perm:[2,3,0,1] row_mask:0xf bank_mask:0xf bound_ctrl:1
	v_pk_mul_f16 v155, v217, v144
	v_pk_mul_f16 v156, v217, v145
	v_add_f32_dpp v151, v151, v151 row_half_mirror row_mask:0xf bank_mask:0xf bound_ctrl:1
	v_cvt_pkrtz_f16_f32 v152, -v151, -v151
	v_pk_fma_f16 v153, v152, v138, v153
	v_pk_fma_f16 v154, v152, v139, v154
	v_pk_fma_f16 v155, v152, v140, v155
	v_pk_fma_f16 v156, v152, v141, v156
	v_pk_fma_f16 v127, v127, v130, v153
	v_pk_fma_f16 v126, v126, v131, v154
	v_pk_fma_f16 v125, v125, v132, v155
	v_pk_fma_f16 v124, v124, v133, v156
	v_dot2_f32_f16 v158, v127, v146, 0
	v_dot2_f32_f16 v158, v126, v147, v158
	v_dot2_f32_f16 v158, v125, v148, v158
	v_dot2_f32_f16 v158, v124, v149, v158
	s_nop 2
	ds_write2st64_b32 v116, v157, v158 offset0:112 offset1:120
	s_xor_b32 s100, s100, 0xe100
	s_cmpk_lg_i32 s30, 0x80
	s_cbranch_scc0 .LBB0_1250
	s_mov_b32 s4, s30
	s_and_saveexec_b64 s[18:19], s[10:11]
	s_cbranch_execnz .LBB0_1229
	s_branch .LBB0_1230
